# static s_setprio 1 for waves 4-7 during the FFT phase (one high-priority wave per SIMD)
# baseline (speedup 1.0000x reference)
.LBB0_195:
	s_and_b64 vcc, exec, s[0:1]
	s_cbranch_vccz .LBB0_238
	v_lshrrev_b32_e32 v146, 6, v163
	s_nop 0
	v_readfirstlane_b32 s1, v146
	s_cmp_lt_u32 s1, 4
	s_cbranch_scc1 .Lfft_noprio
	s_setprio 1
.Lfft_noprio:
	v_readlane_b32 s0, v250, 35
	v_readlane_b32 s1, v250, 36
	v_mov_b32_e32 v146, v163
	s_andn2_b64 vcc, exec, s[0:1]
	s_mov_b32 s0, s92
	s_cbranch_vccnz .LBB0_238

.LBB0_238:
	s_setprio 0
	s_mov_b64 s[0:1], 0
